# HM head-norm streaming split 1 window in the barrier idle time / 3 windows in attention items 0-2
# speedup vs baseline: 1.0024x; 1.0024x over previous
; __device__ __forceinline__ void st_wt16(void* p, u32x4 v) { asm volatile("global_store_dwordx4 %0, %1, off sc1\n\ts_nop 1" : : "v"(p), "v"(v) : "memory"); }
; __device__ __forceinline__ void p5_fixup(const Params& p) {
;     ...
;     for (int v0 = gtid; v0 < T_TOK * 128; v0 += 4 * gsz) {
;         u32x4 hv[4]; float4 s0[4], s1[4];
; #pragma unroll
;         for (int u = 0; u < 4; ++u) { const int v = v0 + u * gsz; if (v < T_TOK * 128) { const int row = v >> 7, head = (v >> 5) & 3;
;             hv[u] = __builtin_nontemporal_load((const u32x4*)(HM + (size_t)v * 8)); s0[u] = *(const float4*)(SSQ + ((size_t)row * 4 + head) * 8); s1[u] = *(const float4*)(SSQ + ((size_t)row * 4 + head) * 8 + 4); } }
; #pragma unroll
;         for (int u = 0; u < 4; ++u) { const int v = v0 + u * gsz; if (v < T_TOK * 128) {
;             const float ss = (s0[u].x + s0[u].y) + (s0[u].z + s0[u].w) + (s1[u].x + s1[u].y) + (s1[u].z + s1[u].w);
;             const float rstd = rsqrtf(ss * (1.0f / 256.0f) + EPS);
;             float f[8]; unpack8(hv[u], f);
; #pragma unroll
;             for (int e = 0; e < 8; ++e) f[e] *= rstd;
;             st_wt16(HM + (size_t)v * 8, pack8(f)); } }
.Lattn_perm_done:
	s_mov_b32 s99, 0
	s_cmp_lt_i32 s90, 6
	s_cselect_b64 s[0:1], -1, 0
	s_and_b64 s[96:97], s[0:1], s[2:3]
	s_andn2_b64 vcc, exec, s[96:97]
	s_cbranch_vccnz .LBB0_629
	s_cmp_eq_u32 s82, 0x100
	s_cbranch_scc0 .Lf4_done
	v_readlane_b32 s96, v254, 23
	v_readlane_b32 s97, v254, 24
	v_lshlrev_b32_e32 v64, 4, v212
	v_mov_b32_e32 v65, s84
	v_lshl_add_u32 v64, v65, 15, v64
	v_lshlrev_b32_e32 v65, 11, v65
	v_and_b32_e32 v60, 0x1e0, v212
	v_add_u32_e32 v65, v65, v60
	v_and_b32_e32 v60, 7, v212
	v_lshl_add_u32 v65, v60, 2, v65
	v_add_u32_e32 v65, 0xfd80000, v65
	s_nop 4
	v_mov_b32_e32 v62, v64
	global_load_dwordx4 v[20:23], v62, s[96:97] nt
	v_add_u32_e32 v62, 0x2000, v64
	global_load_dwordx4 v[24:27], v62, s[96:97] nt
	v_add_u32_e32 v62, 0x4000, v64
	global_load_dwordx4 v[28:31], v62, s[96:97] nt
	v_add_u32_e32 v62, 0x6000, v64
	global_load_dwordx4 v[32:35], v62, s[96:97] nt
	v_mov_b32_e32 v62, v65
	global_load_dword v52, v62, s[88:89]
	v_add_u32_e32 v62, 0x200, v65
	global_load_dword v53, v62, s[88:89]
	v_add_u32_e32 v62, 0x400, v65
	global_load_dword v54, v62, s[88:89]
	v_add_u32_e32 v62, 0x600, v65
	global_load_dword v55, v62, s[88:89]
	s_waitcnt vmcnt(0)
	v_add_f32_dpp v52, v52, v52 quad_perm:[1,0,3,2] row_mask:0xf bank_mask:0xf
	v_add_f32_dpp v53, v53, v53 quad_perm:[1,0,3,2] row_mask:0xf bank_mask:0xf
	v_add_f32_dpp v54, v54, v54 quad_perm:[1,0,3,2] row_mask:0xf bank_mask:0xf
	v_add_f32_dpp v55, v55, v55 quad_perm:[1,0,3,2] row_mask:0xf bank_mask:0xf
	v_add_f32_dpp v52, v52, v52 quad_perm:[2,3,0,1] row_mask:0xf bank_mask:0xf
	v_add_f32_dpp v53, v53, v53 quad_perm:[2,3,0,1] row_mask:0xf bank_mask:0xf
	v_add_f32_dpp v54, v54, v54 quad_perm:[2,3,0,1] row_mask:0xf bank_mask:0xf
	v_add_f32_dpp v55, v55, v55 quad_perm:[2,3,0,1] row_mask:0xf bank_mask:0xf
	v_add_f32_dpp v52, v52, v52 row_half_mirror row_mask:0xf bank_mask:0xf
	v_add_f32_dpp v53, v53, v53 row_half_mirror row_mask:0xf bank_mask:0xf
	v_add_f32_dpp v54, v54, v54 row_half_mirror row_mask:0xf bank_mask:0xf
	v_add_f32_dpp v55, v55, v55 row_half_mirror row_mask:0xf bank_mask:0xf
	v_mov_b32_e32 v60, 0x358637bd
	v_fmamk_f32 v52, v52, 0x3b800000, v60
	v_fmamk_f32 v53, v53, 0x3b800000, v60
	v_fmamk_f32 v54, v54, 0x3b800000, v60
	v_fmamk_f32 v55, v55, 0x3b800000, v60
	v_rsq_f32_e32 v52, v52
	v_rsq_f32_e32 v53, v53
	v_rsq_f32_e32 v54, v54
	v_rsq_f32_e32 v55, v55
	s_nop 0
	v_lshlrev_b32_e32 v62, 16, v20
	v_and_b32_e32 v63, 0xffff0000, v20
	v_mul_f32_e32 v62, v52, v62
	v_mul_f32_e32 v63, v52, v63
	v_cvt_pk_bf16_f32 v20, v62, v63
	v_lshlrev_b32_e32 v62, 16, v21
	v_and_b32_e32 v63, 0xffff0000, v21
	v_mul_f32_e32 v62, v52, v62
	v_mul_f32_e32 v63, v52, v63
	v_cvt_pk_bf16_f32 v21, v62, v63
	v_lshlrev_b32_e32 v62, 16, v22
	v_and_b32_e32 v63, 0xffff0000, v22
	v_mul_f32_e32 v62, v52, v62
	v_mul_f32_e32 v63, v52, v63
	v_cvt_pk_bf16_f32 v22, v62, v63
	v_lshlrev_b32_e32 v62, 16, v23
	v_and_b32_e32 v63, 0xffff0000, v23
	v_mul_f32_e32 v62, v52, v62
	v_mul_f32_e32 v63, v52, v63
	v_cvt_pk_bf16_f32 v23, v62, v63
	v_mov_b32_e32 v62, v64
	global_store_dwordx4 v62, v[20:23], s[96:97]
	v_lshlrev_b32_e32 v62, 16, v24
	v_and_b32_e32 v63, 0xffff0000, v24
	v_mul_f32_e32 v62, v53, v62
	v_mul_f32_e32 v63, v53, v63
	v_cvt_pk_bf16_f32 v24, v62, v63
	v_lshlrev_b32_e32 v62, 16, v25
	v_and_b32_e32 v63, 0xffff0000, v25
	v_mul_f32_e32 v62, v53, v62
	v_mul_f32_e32 v63, v53, v63
	v_cvt_pk_bf16_f32 v25, v62, v63
	v_lshlrev_b32_e32 v62, 16, v26
	v_and_b32_e32 v63, 0xffff0000, v26
	v_mul_f32_e32 v62, v53, v62
	v_mul_f32_e32 v63, v53, v63
	v_cvt_pk_bf16_f32 v26, v62, v63
	v_lshlrev_b32_e32 v62, 16, v27
	v_and_b32_e32 v63, 0xffff0000, v27
	v_mul_f32_e32 v62, v53, v62
	v_mul_f32_e32 v63, v53, v63
	v_cvt_pk_bf16_f32 v27, v62, v63
	v_add_u32_e32 v62, 0x2000, v64
	global_store_dwordx4 v62, v[24:27], s[96:97]
	v_lshlrev_b32_e32 v62, 16, v28
	v_and_b32_e32 v63, 0xffff0000, v28
	v_mul_f32_e32 v62, v54, v62
	v_mul_f32_e32 v63, v54, v63
	v_cvt_pk_bf16_f32 v28, v62, v63
	v_lshlrev_b32_e32 v62, 16, v29
	v_and_b32_e32 v63, 0xffff0000, v29
	v_mul_f32_e32 v62, v54, v62
	v_mul_f32_e32 v63, v54, v63
	v_cvt_pk_bf16_f32 v29, v62, v63
	v_lshlrev_b32_e32 v62, 16, v30
	v_and_b32_e32 v63, 0xffff0000, v30
	v_mul_f32_e32 v62, v54, v62
	v_mul_f32_e32 v63, v54, v63
	v_cvt_pk_bf16_f32 v30, v62, v63
	v_lshlrev_b32_e32 v62, 16, v31
	v_and_b32_e32 v63, 0xffff0000, v31
	v_mul_f32_e32 v62, v54, v62
	v_mul_f32_e32 v63, v54, v63
	v_cvt_pk_bf16_f32 v31, v62, v63
	v_add_u32_e32 v62, 0x4000, v64
	global_store_dwordx4 v62, v[28:31], s[96:97]
	v_lshlrev_b32_e32 v62, 16, v32
	v_and_b32_e32 v63, 0xffff0000, v32
	v_mul_f32_e32 v62, v55, v62
	v_mul_f32_e32 v63, v55, v63
	v_cvt_pk_bf16_f32 v32, v62, v63
	v_lshlrev_b32_e32 v62, 16, v33
	v_and_b32_e32 v63, 0xffff0000, v33
	v_mul_f32_e32 v62, v55, v62
	v_mul_f32_e32 v63, v55, v63
	v_cvt_pk_bf16_f32 v33, v62, v63
	v_lshlrev_b32_e32 v62, 16, v34
	v_and_b32_e32 v63, 0xffff0000, v34
	v_mul_f32_e32 v62, v55, v62
	v_mul_f32_e32 v63, v55, v63
	v_cvt_pk_bf16_f32 v34, v62, v63
	v_lshlrev_b32_e32 v62, 16, v35
	v_and_b32_e32 v63, 0xffff0000, v35
	v_mul_f32_e32 v62, v55, v62
	v_mul_f32_e32 v63, v55, v63
	v_cvt_pk_bf16_f32 v35, v62, v63
	v_add_u32_e32 v62, 0x6000, v64
	global_store_dwordx4 v62, v[32:35], s[96:97]
	s_nop 1

; __device__ __forceinline__ void p5_fixup(const Params& p) {
;     ...
;     const int gtid = bid * 512 + tid, gsz = G * 512;
;     for (int v0 = gtid; v0 < T_TOK * 128; v0 += 4 * gsz) {
;         u32x4 hv[4]; float4 s0[4], s1[4];
; #pragma unroll
;         for (int u = 0; u < 4; ++u) { const int v = v0 + u * gsz; if (v < T_TOK * 128) { const int row = v >> 7, head = (v >> 5) & 3;
;             hv[u] = __builtin_nontemporal_load((const u32x4*)(HM + (size_t)v * 8)); s0[u] = *(const float4*)(SSQ + ((size_t)row * 4 + head) * 8); s1[u] = *(const float4*)(SSQ + ((size_t)row * 4 + head) * 8 + 4); } }
.Lprio5_done:
	s_movk_i32 s98, 0x64
	s_cmp_lg_u32 s82, 0x100
	s_cbranch_scc1 .Lhm_nofuse
	s_mov_b32 s98, 0
	s_mov_b32 s99, 1
	v_readlane_b32 s100, v254, 23
	v_readlane_b32 s101, v254, 24
	v_lshlrev_b32_e32 v250, 4, v212
	v_mov_b32_e32 v251, s84
	v_lshl_add_u32 v250, v251, 15, v250
	v_lshlrev_b32_e32 v251, 11, v251
	v_and_b32_e32 v252, 0x1e0, v212
	v_add_u32_e32 v251, v251, v252
	v_and_b32_e32 v252, 7, v212
	v_lshl_add_u32 v251, v252, 2, v251
	v_add_u32_e32 v251, 0xfe00000, v251
	v_add_u32_e32 v250, 0x800000, v250

; __device__ __forceinline__ void p5_fixup(const Params& p) {
;     ...
;         for (int u = 0; u < 4; ++u) { const int v = v0 + u * gsz; if (v < T_TOK * 128) { const int row = v >> 7, head = (v >> 5) & 3;
;             hv[u] = __builtin_nontemporal_load((const u32x4*)(HM + (size_t)v * 8)); s0[u] = *(const float4*)(SSQ + ((size_t)row * 4 + head) * 8); s1[u] = *(const float4*)(SSQ + ((size_t)row * 4 + head) * 8 + 4); } }
.Lat_norope:
	s_or_b64 exec, exec, s[0:1]
	s_cmp_gt_u32 s98, 2
	s_cbranch_scc1 .Lhm_noissue
	v_mov_b32_e32 v252, s98
	v_lshl_add_u32 v255, v252, 23, v250
	v_lshl_add_u32 v252, v252, 19, v251
	global_load_dwordx4 v[230:233], v255, s[100:101] nt
	v_add_u32_e32 v255, 0x2000, v255
	global_load_dwordx4 v[234:237], v255, s[100:101] nt
	v_add_u32_e32 v255, 0x2000, v255
	global_load_dwordx4 v[238:241], v255, s[100:101] nt
	v_add_u32_e32 v255, 0x2000, v255
	global_load_dwordx4 v[242:245], v255, s[100:101] nt
	global_load_dword v246, v252, s[88:89]
	global_load_dword v247, v252, s[88:89] offset:512
	global_load_dword v248, v252, s[88:89] offset:1024
	global_load_dword v249, v252, s[88:89] offset:1536
	s_waitcnt vmcnt(8)
	s_branch .Lhm_issued

; __device__ __forceinline__ void st_wt16(void* p, u32x4 v) { asm volatile("global_store_dwordx4 %0, %1, off sc1\n\ts_nop 1" : : "v"(p), "v"(v) : "memory"); }
; __device__ __forceinline__ void p5_fixup(const Params& p) {
;     ...
;         for (int u = 0; u < 4; ++u) { const int v = v0 + u * gsz; if (v < T_TOK * 128) {
;             const float ss = (s0[u].x + s0[u].y) + (s0[u].z + s0[u].w) + (s1[u].x + s1[u].y) + (s1[u].z + s1[u].w);
;             const float rstd = rsqrtf(ss * (1.0f / 256.0f) + EPS);
;             float f[8]; unpack8(hv[u], f);
; #pragma unroll
;             for (int e = 0; e < 8; ++e) f[e] *= rstd;
;             st_wt16(HM + (size_t)v * 8, pack8(f)); } }
.Lattn_pf_done:
	s_cmp_gt_u32 s98, 2
	s_cbranch_scc1 .Lhm_noconsume
	v_add_f32_dpp v246, v246, v246 quad_perm:[1,0,3,2] row_mask:0xf bank_mask:0xf
	v_add_f32_dpp v247, v247, v247 quad_perm:[1,0,3,2] row_mask:0xf bank_mask:0xf
	v_add_f32_dpp v248, v248, v248 quad_perm:[1,0,3,2] row_mask:0xf bank_mask:0xf
	v_add_f32_dpp v249, v249, v249 quad_perm:[1,0,3,2] row_mask:0xf bank_mask:0xf
	v_add_f32_dpp v246, v246, v246 quad_perm:[2,3,0,1] row_mask:0xf bank_mask:0xf
	v_add_f32_dpp v247, v247, v247 quad_perm:[2,3,0,1] row_mask:0xf bank_mask:0xf
	v_add_f32_dpp v248, v248, v248 quad_perm:[2,3,0,1] row_mask:0xf bank_mask:0xf
	v_add_f32_dpp v249, v249, v249 quad_perm:[2,3,0,1] row_mask:0xf bank_mask:0xf
	v_add_f32_dpp v246, v246, v246 row_half_mirror row_mask:0xf bank_mask:0xf
	v_add_f32_dpp v247, v247, v247 row_half_mirror row_mask:0xf bank_mask:0xf
	v_add_f32_dpp v248, v248, v248 row_half_mirror row_mask:0xf bank_mask:0xf
	v_add_f32_dpp v249, v249, v249 row_half_mirror row_mask:0xf bank_mask:0xf
	v_mov_b32_e32 v252, 0x358637bd
	v_mov_b32_e32 v255, s98
	v_fmamk_f32 v246, v246, 0x3b800000, v252
	v_fmamk_f32 v247, v247, 0x3b800000, v252
	v_fmamk_f32 v248, v248, 0x3b800000, v252
	v_fmamk_f32 v249, v249, 0x3b800000, v252
	v_rsq_f32_e32 v246, v246
	v_rsq_f32_e32 v247, v247
	v_rsq_f32_e32 v248, v248
	v_rsq_f32_e32 v249, v249
	v_lshl_add_u32 v255, v255, 23, v250
	v_lshlrev_b32_e32 v252, 16, v230
	v_and_b32_e32 v253, 0xffff0000, v230
	v_mul_f32_e32 v252, v246, v252
	v_mul_f32_e32 v253, v246, v253
	v_cvt_pk_bf16_f32 v230, v252, v253
	v_lshlrev_b32_e32 v252, 16, v231
	v_and_b32_e32 v253, 0xffff0000, v231
	v_mul_f32_e32 v252, v246, v252
	v_mul_f32_e32 v253, v246, v253
	v_cvt_pk_bf16_f32 v231, v252, v253
	v_lshlrev_b32_e32 v252, 16, v232
	v_and_b32_e32 v253, 0xffff0000, v232
	v_mul_f32_e32 v252, v246, v252
	v_mul_f32_e32 v253, v246, v253
	v_cvt_pk_bf16_f32 v232, v252, v253
	v_lshlrev_b32_e32 v252, 16, v233
	v_and_b32_e32 v253, 0xffff0000, v233
	v_mul_f32_e32 v252, v246, v252
	v_mul_f32_e32 v253, v246, v253
	v_cvt_pk_bf16_f32 v233, v252, v253
	global_store_dwordx4 v255, v[230:233], s[100:101]
	v_add_u32_e32 v255, 0x2000, v255
	v_lshlrev_b32_e32 v252, 16, v234
	v_and_b32_e32 v253, 0xffff0000, v234
	v_mul_f32_e32 v252, v247, v252
	v_mul_f32_e32 v253, v247, v253
	v_cvt_pk_bf16_f32 v234, v252, v253
	v_lshlrev_b32_e32 v252, 16, v235
	v_and_b32_e32 v253, 0xffff0000, v235
	v_mul_f32_e32 v252, v247, v252
	v_mul_f32_e32 v253, v247, v253
	v_cvt_pk_bf16_f32 v235, v252, v253
	v_lshlrev_b32_e32 v252, 16, v236
	v_and_b32_e32 v253, 0xffff0000, v236
	v_mul_f32_e32 v252, v247, v252
	v_mul_f32_e32 v253, v247, v253
	v_cvt_pk_bf16_f32 v236, v252, v253
	v_lshlrev_b32_e32 v252, 16, v237
	v_and_b32_e32 v253, 0xffff0000, v237
	v_mul_f32_e32 v252, v247, v252
	v_mul_f32_e32 v253, v247, v253
	v_cvt_pk_bf16_f32 v237, v252, v253
	global_store_dwordx4 v255, v[234:237], s[100:101]
	v_add_u32_e32 v255, 0x2000, v255
	v_lshlrev_b32_e32 v252, 16, v238
	v_and_b32_e32 v253, 0xffff0000, v238
	v_mul_f32_e32 v252, v248, v252
	v_mul_f32_e32 v253, v248, v253
	v_cvt_pk_bf16_f32 v238, v252, v253
	v_lshlrev_b32_e32 v252, 16, v239
	v_and_b32_e32 v253, 0xffff0000, v239
	v_mul_f32_e32 v252, v248, v252
	v_mul_f32_e32 v253, v248, v253
	v_cvt_pk_bf16_f32 v239, v252, v253
	v_lshlrev_b32_e32 v252, 16, v240
	v_and_b32_e32 v253, 0xffff0000, v240
	v_mul_f32_e32 v252, v248, v252
	v_mul_f32_e32 v253, v248, v253
	v_cvt_pk_bf16_f32 v240, v252, v253
	v_lshlrev_b32_e32 v252, 16, v241
	v_and_b32_e32 v253, 0xffff0000, v241
	v_mul_f32_e32 v252, v248, v252
	v_mul_f32_e32 v253, v248, v253
	v_cvt_pk_bf16_f32 v241, v252, v253
	global_store_dwordx4 v255, v[238:241], s[100:101]
	v_add_u32_e32 v255, 0x2000, v255
	v_lshlrev_b32_e32 v252, 16, v242
	v_and_b32_e32 v253, 0xffff0000, v242
	v_mul_f32_e32 v252, v249, v252
	v_mul_f32_e32 v253, v249, v253
	v_cvt_pk_bf16_f32 v242, v252, v253
	v_lshlrev_b32_e32 v252, 16, v243
	v_and_b32_e32 v253, 0xffff0000, v243
	v_mul_f32_e32 v252, v249, v252
	v_mul_f32_e32 v253, v249, v253
	v_cvt_pk_bf16_f32 v243, v252, v253
	v_lshlrev_b32_e32 v252, 16, v244
	v_and_b32_e32 v253, 0xffff0000, v244
	v_mul_f32_e32 v252, v249, v252
	v_mul_f32_e32 v253, v249, v253
	v_cvt_pk_bf16_f32 v244, v252, v253
	v_lshlrev_b32_e32 v252, 16, v245
	v_and_b32_e32 v253, 0xffff0000, v245
	v_mul_f32_e32 v252, v249, v252
	v_mul_f32_e32 v253, v249, v253
	v_cvt_pk_bf16_f32 v245, v252, v253
	global_store_dwordx4 v255, v[242:245], s[100:101]
	s_nop 1
